# grid barrier: leaders and waiters poll the top arrival counter (one atomic round trip less); on top of v34
# speedup vs baseline: 1.0389x; 1.0009x over previous
; __device__ __forceinline__ unsigned xb_ld(unsigned* p)              { return __hip_atomic_load(p, __ATOMIC_RELAXED, __HIP_MEMORY_SCOPE_AGENT); }
; __device__ __forceinline__ unsigned xb_add(unsigned* p, unsigned v) { return __hip_atomic_fetch_add(p, v, __ATOMIC_RELAXED, __HIP_MEMORY_SCOPE_AGENT); }
; #define XB_SPIN(cond, bar) do { unsigned _sp = 0; while (cond) { __builtin_amdgcn_s_sleep(1); \
;     if ((++_sp & 255u) == 0u) { if (xb_ld(&(bar)[XB_TMO])) break; if (_sp > XB_SPIN_CAP) { atomicAdd(&(bar)[XB_TMO], 1u); break; } } } } while (0)
; __device__ __forceinline__ void xcd_barrier(const XcdBarrier& b) {
;     ...
;         const unsigned old = xb_add(&bar[XB_XSUB(b.x)], 1u);
;         const unsigned gen = old / nloc;
;         if (old + 1u == (gen + 1u) * nloc) {
;     ...
;         } else {
;             XB_SPIN(xb_ld(&bar[XB_XGEN(b.x)]) == gen, bar);
;             __builtin_amdgcn_fence(__ATOMIC_ACQUIRE, "agent");
;             asm volatile("s_waitcnt vmcnt(0)" ::: "memory");
;         }
.LBB0_200:
	s_or_b64 exec, exec, s[10:11]
	v_cvt_f32_u32_e32 v4, v2
	s_waitcnt vmcnt(0)
	v_readfirstlane_b32 s0, v3
	v_sub_u32_e32 v3, 0, v2
	v_rcp_iflag_f32_e32 v4, v4
	v_add_u32_e32 v5, s0, v1
	v_mul_f32_e32 v4, 0x4f7ffffe, v4
	v_cvt_u32_f32_e32 v4, v4
	v_mul_lo_u32 v1, v3, v4
	v_mul_hi_u32 v1, v4, v1
	v_add_u32_e32 v1, v4, v1
	v_mul_hi_u32 v1, v5, v1
	v_mul_lo_u32 v3, v1, v2
	v_sub_u32_e32 v3, v5, v3
	v_add_u32_e32 v4, 1, v1
	v_cmp_ge_u32_e32 vcc, v3, v2
	s_nop 1
	v_cndmask_b32_e32 v1, v1, v4, vcc
	v_sub_u32_e32 v4, v3, v2
	v_cndmask_b32_e32 v3, v3, v4, vcc
	v_add_u32_e32 v4, 1, v1
	v_cmp_ge_u32_e32 vcc, v3, v2
	v_add_u32_e32 v3, 1, v5
	s_nop 0
	v_cndmask_b32_e32 v1, v1, v4, vcc
	v_mul_lo_u32 v4, v2, v1
	v_add_u32_e32 v2, v4, v2
	v_cmp_ne_u32_e32 vcc, v3, v2
	s_and_saveexec_b64 s[0:1], vcc
	s_xor_b64 s[8:9], exec, s[0:1]
	s_cbranch_execz .LBB0_214
	s_waitcnt lgkmcnt(0)
	v_add_u32_e32 v1, 1, v1
	v_mul_lo_u32 v1, v1, v0
	v_mov_b32_e32 v0, 0x3000
	global_load_dword v0, v0, s[78:79] offset:1024 sc1
	s_add_u32 s14, s78, 0x3400
	s_addc_u32 s15, s79, 0
	s_waitcnt vmcnt(0)
	v_cmp_lt_u32_e32 vcc, v0, v1
	s_and_saveexec_b64 s[10:11], vcc
	s_cbranch_execz .LBB0_213
	s_mov_b32 s0, 1
	s_mov_b64 s[16:17], 0
	v_mov_b32_e32 v0, 0
	s_branch .LBB0_204

; __device__ __forceinline__ unsigned xb_ld(unsigned* p)              { return __hip_atomic_load(p, __ATOMIC_RELAXED, __HIP_MEMORY_SCOPE_AGENT); }
; #define XB_SPIN(cond, bar) do { unsigned _sp = 0; while (cond) { __builtin_amdgcn_s_sleep(1); \
;     if ((++_sp & 255u) == 0u) { if (xb_ld(&(bar)[XB_TMO])) break; if (_sp > XB_SPIN_CAP) { atomicAdd(&(bar)[XB_TMO], 1u); break; } } } } while (0)
; __device__ __forceinline__ void xcd_barrier(const XcdBarrier& b) {
;     ...
;             XB_SPIN(xb_ld(&bar[XB_XGEN(b.x)]) == gen, bar);
.LBB0_208:
	global_load_dword v2, v0, s[14:15] sc1
	s_add_i32 s0, s0, 1
	s_mov_b64 s[22:23], -1
	s_waitcnt vmcnt(0)
	v_cmp_ge_u32_e32 vcc, v2, v1
	s_orn2_b64 s[20:21], vcc, exec
	s_branch .LBB0_203

; __device__ __forceinline__ unsigned xb_ld(unsigned* p)              { return __hip_atomic_load(p, __ATOMIC_RELAXED, __HIP_MEMORY_SCOPE_AGENT); }
; __device__ __forceinline__ unsigned xb_add(unsigned* p, unsigned v) { return __hip_atomic_fetch_add(p, v, __ATOMIC_RELAXED, __HIP_MEMORY_SCOPE_AGENT); }
; #define XB_SPIN(cond, bar) do { unsigned _sp = 0; while (cond) { __builtin_amdgcn_s_sleep(1); \
;     if ((++_sp & 255u) == 0u) { if (xb_ld(&(bar)[XB_TMO])) break; if (_sp > XB_SPIN_CAP) { atomicAdd(&(bar)[XB_TMO], 1u); break; } } } } while (0)
; __device__ __forceinline__ void xcd_barrier(const XcdBarrier& b) {
;     ...
;         if (old + 1u == (gen + 1u) * nloc) {
;             __builtin_amdgcn_fence(__ATOMIC_RELEASE, "agent");
;             asm volatile("s_waitcnt vmcnt(0)" ::: "memory");
;             const unsigned og = xb_add(&bar[XB_TOP], 1u);
;             const unsigned tg = og / nx;
;             if (og + 1u == (tg + 1u) * nx) xb_add(&bar[XB_TOPGEN], 1u);
;             else XB_SPIN(xb_ld(&bar[XB_TOPGEN]) == tg, bar);
.LBB0_217:
	s_or_b64 exec, exec, s[10:11]
	v_cvt_f32_u32_e32 v3, v0
	s_waitcnt vmcnt(0)
	v_readfirstlane_b32 s0, v2
	s_add_u32 s10, s78, 0x3500
	s_addc_u32 s11, s79, 0
	v_rcp_iflag_f32_e32 v3, v3
	v_add_u32_e32 v1, s0, v1
	v_add_u32_e32 v4, 1, v1
	s_mov_b64 s[14:15], -1
	v_mul_f32_e32 v2, 0x4f7ffffe, v3
	v_cvt_u32_f32_e32 v2, v2
	v_sub_u32_e32 v3, 0, v0
	v_mul_lo_u32 v3, v3, v2
	v_mul_hi_u32 v3, v2, v3
	v_add_u32_e32 v2, v2, v3
	v_mul_hi_u32 v2, v1, v2
	v_mul_lo_u32 v3, v2, v0
	v_sub_u32_e32 v1, v1, v3
	v_add_u32_e32 v5, 1, v2
	v_cmp_ge_u32_e32 vcc, v1, v0
	v_sub_u32_e32 v3, v1, v0
	s_nop 0
	v_cndmask_b32_e32 v2, v2, v5, vcc
	v_cndmask_b32_e32 v1, v1, v3, vcc
	v_add_u32_e32 v3, 1, v2
	v_cmp_ge_u32_e32 vcc, v1, v0
	s_nop 1
	v_cndmask_b32_e32 v2, v2, v3, vcc
	v_mul_lo_u32 v1, v0, v2
	v_add_u32_e32 v0, v1, v0
	v_cmp_ne_u32_e32 vcc, v4, v0
	v_mov_b32_e32 v2, v0
	v_mov_b64_e32 v[0:1], s[10:11]
	s_and_saveexec_b64 s[8:9], vcc
	s_cbranch_execz .LBB0_229
	v_mov_b32_e32 v0, 0
	global_load_dword v1, v0, s[10:11] offset:-256 sc1
	s_mov_b64 s[18:19], 0
	s_waitcnt vmcnt(0)
	v_cmp_lt_u32_e32 vcc, v1, v2
	s_and_saveexec_b64 s[16:17], vcc
	s_cbranch_execz .LBB0_228
	s_add_u32 s14, s78, 0x200
	s_addc_u32 s15, s79, 0
	s_mov_b32 s0, 1
	s_branch .LBB0_221

; __device__ __forceinline__ unsigned xb_ld(unsigned* p)              { return __hip_atomic_load(p, __ATOMIC_RELAXED, __HIP_MEMORY_SCOPE_AGENT); }
; #define XB_SPIN(cond, bar) do { unsigned _sp = 0; while (cond) { __builtin_amdgcn_s_sleep(1); \
;     if ((++_sp & 255u) == 0u) { if (xb_ld(&(bar)[XB_TMO])) break; if (_sp > XB_SPIN_CAP) { atomicAdd(&(bar)[XB_TMO], 1u); break; } } } } while (0)
; __device__ __forceinline__ void xcd_barrier(const XcdBarrier& b) {
;     ...
;             else XB_SPIN(xb_ld(&bar[XB_TOPGEN]) == tg, bar);
.LBB0_225:
	global_load_dword v1, v0, s[10:11] offset:-256 sc1
	s_add_i32 s0, s0, 1
	s_mov_b64 s[22:23], -1
	s_waitcnt vmcnt(0)
	v_cmp_ge_u32_e32 vcc, v1, v2
	s_orn2_b64 s[26:27], vcc, exec
	s_branch .LBB0_220

; __device__ __forceinline__ unsigned xb_ld(unsigned* p)              { return __hip_atomic_load(p, __ATOMIC_RELAXED, __HIP_MEMORY_SCOPE_AGENT); }
; __device__ __forceinline__ unsigned xb_add(unsigned* p, unsigned v) { return __hip_atomic_fetch_add(p, v, __ATOMIC_RELAXED, __HIP_MEMORY_SCOPE_AGENT); }
; #define XB_SPIN(cond, bar) do { unsigned _sp = 0; while (cond) { __builtin_amdgcn_s_sleep(1); \
;     if ((++_sp & 255u) == 0u) { if (xb_ld(&(bar)[XB_TMO])) break; if (_sp > XB_SPIN_CAP) { atomicAdd(&(bar)[XB_TMO], 1u); break; } } } } while (0)
; __device__ __forceinline__ void xcd_barrier(const XcdBarrier& b) {
;     ...
;         const unsigned old = xb_add(&bar[XB_XSUB(b.x)], 1u);
;         const unsigned gen = old / nloc;
;         if (old + 1u == (gen + 1u) * nloc) {
;     ...
;         } else {
;             XB_SPIN(xb_ld(&bar[XB_XGEN(b.x)]) == gen, bar);
;             __builtin_amdgcn_fence(__ATOMIC_ACQUIRE, "agent");
;             asm volatile("s_waitcnt vmcnt(0)" ::: "memory");
;         }
.LBB0_557:
	s_or_b64 exec, exec, s[10:11]
	v_cvt_f32_u32_e32 v4, v2
	s_waitcnt vmcnt(0)
	v_readfirstlane_b32 s0, v3
	v_sub_u32_e32 v3, 0, v2
	v_rcp_iflag_f32_e32 v4, v4
	v_add_u32_e32 v5, s0, v1
	v_mul_f32_e32 v4, 0x4f7ffffe, v4
	v_cvt_u32_f32_e32 v4, v4
	v_mul_lo_u32 v1, v3, v4
	v_mul_hi_u32 v1, v4, v1
	v_add_u32_e32 v1, v4, v1
	v_mul_hi_u32 v1, v5, v1
	v_mul_lo_u32 v3, v1, v2
	v_sub_u32_e32 v3, v5, v3
	v_add_u32_e32 v4, 1, v1
	v_cmp_ge_u32_e32 vcc, v3, v2
	s_nop 1
	v_cndmask_b32_e32 v1, v1, v4, vcc
	v_sub_u32_e32 v4, v3, v2
	v_cndmask_b32_e32 v3, v3, v4, vcc
	v_add_u32_e32 v4, 1, v1
	v_cmp_ge_u32_e32 vcc, v3, v2
	v_add_u32_e32 v3, 1, v5
	s_nop 0
	v_cndmask_b32_e32 v1, v1, v4, vcc
	v_mul_lo_u32 v4, v2, v1
	v_add_u32_e32 v2, v4, v2
	v_cmp_ne_u32_e32 vcc, v3, v2
	s_and_saveexec_b64 s[0:1], vcc
	s_xor_b64 s[8:9], exec, s[0:1]
	s_cbranch_execz .LBB0_571
	s_waitcnt lgkmcnt(0)
	v_add_u32_e32 v1, 1, v1
	v_mul_lo_u32 v1, v1, v0
	v_mov_b32_e32 v0, 0x3000
	global_load_dword v0, v0, s[78:79] offset:1024 sc1
	s_add_u32 s12, s78, 0x3400
	s_addc_u32 s13, s79, 0
	s_waitcnt vmcnt(0)
	v_cmp_lt_u32_e32 vcc, v0, v1
	s_and_saveexec_b64 s[10:11], vcc
	s_cbranch_execz .LBB0_570
	s_mov_b32 s0, 1
	s_mov_b64 s[14:15], 0
	v_mov_b32_e32 v0, 0
	s_branch .LBB0_561

; __device__ __forceinline__ unsigned xb_ld(unsigned* p)              { return __hip_atomic_load(p, __ATOMIC_RELAXED, __HIP_MEMORY_SCOPE_AGENT); }
; #define XB_SPIN(cond, bar) do { unsigned _sp = 0; while (cond) { __builtin_amdgcn_s_sleep(1); \
;     if ((++_sp & 255u) == 0u) { if (xb_ld(&(bar)[XB_TMO])) break; if (_sp > XB_SPIN_CAP) { atomicAdd(&(bar)[XB_TMO], 1u); break; } } } } while (0)
; __device__ __forceinline__ void xcd_barrier(const XcdBarrier& b) {
;     ...
;             XB_SPIN(xb_ld(&bar[XB_XGEN(b.x)]) == gen, bar);
.LBB0_565:
	global_load_dword v2, v0, s[12:13] sc1
	s_add_i32 s0, s0, 1
	s_mov_b64 s[20:21], -1
	s_waitcnt vmcnt(0)
	v_cmp_ge_u32_e32 vcc, v2, v1
	s_orn2_b64 s[18:19], vcc, exec
	s_branch .LBB0_560

; __device__ __forceinline__ unsigned xb_ld(unsigned* p)              { return __hip_atomic_load(p, __ATOMIC_RELAXED, __HIP_MEMORY_SCOPE_AGENT); }
; __device__ __forceinline__ unsigned xb_add(unsigned* p, unsigned v) { return __hip_atomic_fetch_add(p, v, __ATOMIC_RELAXED, __HIP_MEMORY_SCOPE_AGENT); }
; #define XB_SPIN(cond, bar) do { unsigned _sp = 0; while (cond) { __builtin_amdgcn_s_sleep(1); \
;     if ((++_sp & 255u) == 0u) { if (xb_ld(&(bar)[XB_TMO])) break; if (_sp > XB_SPIN_CAP) { atomicAdd(&(bar)[XB_TMO], 1u); break; } } } } while (0)
; __device__ __forceinline__ void xcd_barrier(const XcdBarrier& b) {
;     ...
;         if (old + 1u == (gen + 1u) * nloc) {
;             __builtin_amdgcn_fence(__ATOMIC_RELEASE, "agent");
;             asm volatile("s_waitcnt vmcnt(0)" ::: "memory");
;             const unsigned og = xb_add(&bar[XB_TOP], 1u);
;             const unsigned tg = og / nx;
;             if (og + 1u == (tg + 1u) * nx) xb_add(&bar[XB_TOPGEN], 1u);
;             else XB_SPIN(xb_ld(&bar[XB_TOPGEN]) == tg, bar);
.LBB0_574:
	s_or_b64 exec, exec, s[10:11]
	v_cvt_f32_u32_e32 v3, v0
	s_waitcnt vmcnt(0)
	v_readfirstlane_b32 s0, v2
	s_add_u32 s10, s78, 0x3500
	s_addc_u32 s11, s79, 0
	v_rcp_iflag_f32_e32 v3, v3
	v_add_u32_e32 v1, s0, v1
	v_add_u32_e32 v4, 1, v1
	s_mov_b64 s[12:13], -1
	v_mul_f32_e32 v2, 0x4f7ffffe, v3
	v_cvt_u32_f32_e32 v2, v2
	v_sub_u32_e32 v3, 0, v0
	v_mul_lo_u32 v3, v3, v2
	v_mul_hi_u32 v3, v2, v3
	v_add_u32_e32 v2, v2, v3
	v_mul_hi_u32 v2, v1, v2
	v_mul_lo_u32 v3, v2, v0
	v_sub_u32_e32 v1, v1, v3
	v_add_u32_e32 v5, 1, v2
	v_cmp_ge_u32_e32 vcc, v1, v0
	v_sub_u32_e32 v3, v1, v0
	s_nop 0
	v_cndmask_b32_e32 v2, v2, v5, vcc
	v_cndmask_b32_e32 v1, v1, v3, vcc
	v_add_u32_e32 v3, 1, v2
	v_cmp_ge_u32_e32 vcc, v1, v0
	s_nop 1
	v_cndmask_b32_e32 v2, v2, v3, vcc
	v_mul_lo_u32 v1, v0, v2
	v_add_u32_e32 v0, v1, v0
	v_cmp_ne_u32_e32 vcc, v4, v0
	v_mov_b32_e32 v2, v0
	v_mov_b64_e32 v[0:1], s[10:11]
	s_and_saveexec_b64 s[8:9], vcc
	s_cbranch_execz .LBB0_586
	v_mov_b32_e32 v0, 0
	global_load_dword v1, v0, s[10:11] offset:-256 sc1
	s_mov_b64 s[16:17], 0
	s_waitcnt vmcnt(0)
	v_cmp_lt_u32_e32 vcc, v1, v2
	s_and_saveexec_b64 s[14:15], vcc
	s_cbranch_execz .LBB0_585
	s_add_u32 s12, s78, 0x200
	s_addc_u32 s13, s79, 0
	s_mov_b32 s0, 1
	s_branch .LBB0_578

; __device__ __forceinline__ unsigned xb_ld(unsigned* p)              { return __hip_atomic_load(p, __ATOMIC_RELAXED, __HIP_MEMORY_SCOPE_AGENT); }
; #define XB_SPIN(cond, bar) do { unsigned _sp = 0; while (cond) { __builtin_amdgcn_s_sleep(1); \
;     if ((++_sp & 255u) == 0u) { if (xb_ld(&(bar)[XB_TMO])) break; if (_sp > XB_SPIN_CAP) { atomicAdd(&(bar)[XB_TMO], 1u); break; } } } } while (0)
; __device__ __forceinline__ void xcd_barrier(const XcdBarrier& b) {
;     ...
;             else XB_SPIN(xb_ld(&bar[XB_TOPGEN]) == tg, bar);
.LBB0_582:
	global_load_dword v1, v0, s[10:11] offset:-256 sc1
	s_add_i32 s0, s0, 1
	s_mov_b64 s[20:21], -1
	s_waitcnt vmcnt(0)
	v_cmp_ge_u32_e32 vcc, v1, v2
	s_orn2_b64 s[24:25], vcc, exec
	s_branch .LBB0_577
